# w_in x / gelu(g) epilogue paths rewritten by hand: 16-byte stores, gelu_tanh with folded constants
# speedup vs baseline: 1.0777x; 1.0066x over previous
.LBB0_486:
	s_load_dwordx2 s[14:15], s[0:1], 0xc8
	s_lshr_b32 s13, s57, 5
	s_cmp_gt_u32 s44, 4
	s_cbranch_scc1 .Lwing_g
	s_sub_i32 s8, s44, 3
	s_lshl_b32 s8, s8, 8
	s_or_b32 s8, s8, s57
	s_lshl_b32 s8, s8, 1
	s_lshl_b32 s9, s3, 10
	s_add_u32 s8, s8, s9
	s_add_u32 s8, s8, 0x7700000
	v_lshlrev_b32_e32 v139, 10, v205
	v_lshl_add_u32 v139, v247, 1, v139
	s_waitcnt lgkmcnt(0)
	s_add_u32 s66, s14, s8
	s_addc_u32 s67, s15, 0
	v_cvt_pk_bf16_f32 v126, v126, v127
	v_cvt_pk_bf16_f32 v127, v128, v129
	v_cvt_pk_bf16_f32 v128, v122, v123
	v_cvt_pk_bf16_f32 v129, v124, v125
	global_store_dwordx4 v139, v[126:129], s[66:67]
	v_cvt_pk_bf16_f32 v118, v118, v119
	v_cvt_pk_bf16_f32 v119, v120, v121
	v_cvt_pk_bf16_f32 v120, v114, v115
	v_cvt_pk_bf16_f32 v121, v116, v117
	global_store_dwordx4 v139, v[118:121], s[66:67] offset:256
	s_add_u32 s66, s66, 0x4000
	s_addc_u32 s67, s67, 0
	v_cvt_pk_bf16_f32 v110, v110, v111
	v_cvt_pk_bf16_f32 v111, v112, v113
	v_cvt_pk_bf16_f32 v112, v106, v107
	v_cvt_pk_bf16_f32 v113, v108, v109
	global_store_dwordx4 v139, v[110:113], s[66:67]
	v_cvt_pk_bf16_f32 v102, v102, v103
	v_cvt_pk_bf16_f32 v103, v104, v105
	v_cvt_pk_bf16_f32 v104, v98, v99
	v_cvt_pk_bf16_f32 v105, v100, v101
	global_store_dwordx4 v139, v[102:105], s[66:67] offset:256
	s_add_u32 s66, s66, 0x4000
	s_addc_u32 s67, s67, 0
	v_cvt_pk_bf16_f32 v94, v94, v95
	v_cvt_pk_bf16_f32 v95, v96, v97
	v_cvt_pk_bf16_f32 v96, v90, v91
	v_cvt_pk_bf16_f32 v97, v92, v93
	global_store_dwordx4 v139, v[94:97], s[66:67]
	v_cvt_pk_bf16_f32 v86, v86, v87
	v_cvt_pk_bf16_f32 v87, v88, v89
	v_cvt_pk_bf16_f32 v88, v82, v83
	v_cvt_pk_bf16_f32 v89, v84, v85
	global_store_dwordx4 v139, v[86:89], s[66:67] offset:256
	s_add_u32 s66, s66, 0x4000
	s_addc_u32 s67, s67, 0
	v_cvt_pk_bf16_f32 v78, v78, v79
	v_cvt_pk_bf16_f32 v79, v80, v81
	v_cvt_pk_bf16_f32 v80, v74, v75
	v_cvt_pk_bf16_f32 v81, v76, v77
	global_store_dwordx4 v139, v[78:81], s[66:67]
	v_cvt_pk_bf16_f32 v70, v70, v71
	v_cvt_pk_bf16_f32 v71, v72, v73
	v_cvt_pk_bf16_f32 v72, v66, v67
	v_cvt_pk_bf16_f32 v73, v68, v69
	global_store_dwordx4 v139, v[70:73], s[66:67] offset:256
	s_add_u32 s66, s66, 0x14000
	s_addc_u32 s67, s67, 0
	v_cvt_pk_bf16_f32 v62, v62, v63
	v_cvt_pk_bf16_f32 v63, v64, v65
	v_cvt_pk_bf16_f32 v64, v58, v59
	v_cvt_pk_bf16_f32 v65, v60, v61
	global_store_dwordx4 v139, v[62:65], s[66:67]
	v_cvt_pk_bf16_f32 v54, v54, v55
	v_cvt_pk_bf16_f32 v55, v56, v57
	v_cvt_pk_bf16_f32 v56, v50, v51
	v_cvt_pk_bf16_f32 v57, v52, v53
	global_store_dwordx4 v139, v[54:57], s[66:67] offset:256
	s_add_u32 s66, s66, 0x4000
	s_addc_u32 s67, s67, 0
	v_cvt_pk_bf16_f32 v46, v46, v47
	v_cvt_pk_bf16_f32 v47, v48, v49
	v_cvt_pk_bf16_f32 v48, v42, v43
	v_cvt_pk_bf16_f32 v49, v44, v45
	global_store_dwordx4 v139, v[46:49], s[66:67]
	v_cvt_pk_bf16_f32 v38, v38, v39
	v_cvt_pk_bf16_f32 v39, v40, v41
	v_cvt_pk_bf16_f32 v40, v34, v35
	v_cvt_pk_bf16_f32 v41, v36, v37
	global_store_dwordx4 v139, v[38:41], s[66:67] offset:256
	s_add_u32 s66, s66, 0x4000
	s_addc_u32 s67, s67, 0
	v_cvt_pk_bf16_f32 v30, v30, v31
	v_cvt_pk_bf16_f32 v31, v32, v33
	v_cvt_pk_bf16_f32 v32, v26, v27
	v_cvt_pk_bf16_f32 v33, v28, v29
	global_store_dwordx4 v139, v[30:33], s[66:67]
	v_cvt_pk_bf16_f32 v22, v22, v23
	v_cvt_pk_bf16_f32 v23, v24, v25
	v_cvt_pk_bf16_f32 v24, v18, v19
	v_cvt_pk_bf16_f32 v25, v20, v21
	global_store_dwordx4 v139, v[22:25], s[66:67] offset:256
	s_add_u32 s66, s66, 0x4000
	s_addc_u32 s67, s67, 0
	v_cvt_pk_bf16_f32 v14, v14, v15
	v_cvt_pk_bf16_f32 v15, v16, v17
	v_cvt_pk_bf16_f32 v16, v10, v11
	v_cvt_pk_bf16_f32 v17, v12, v13
	global_store_dwordx4 v139, v[14:17], s[66:67]
	v_cvt_pk_bf16_f32 v6, v6, v7
	v_cvt_pk_bf16_f32 v7, v8, v9
	v_cvt_pk_bf16_f32 v8, v2, v3
	v_cvt_pk_bf16_f32 v9, v4, v5
	global_store_dwordx4 v139, v[6:9], s[66:67] offset:256
	s_branch .Lwing_done
.Lwing_g:
	s_sub_i32 s8, s44, 5
	s_lshl_b32 s8, s8, 2
	s_lshr_b32 s9, s13, 1
	s_add_i32 s8, s8, s9
	s_lshl_b32 s8, s8, 11
	s_and_b32 s9, s13, 1
	s_lshl_b32 s9, s9, 10
	s_add_i32 s8, s8, s9
	s_lshr_b32 s9, s3, 4
	s_lshl_b32 s9, s9, 14
	s_add_u32 s8, s8, s9
	s_add_u32 s8, s8, 0x8801000
	v_lshrrev_b32_e32 v139, 4, v247
	v_lshlrev_b32_e32 v139, 9, v139
	v_lshl_add_u32 v139, v205, 5, v139
	v_and_b32_e32 v0, 8, v247
	v_lshl_add_u32 v139, v0, 1, v139
	v_mov_b32_e32 v138, 0xc0135761
	s_waitcnt lgkmcnt(0)
	s_add_u32 s66, s14, s8
	s_addc_u32 s67, s15, 0
	v_mul_f32_e32 v130, v126, v126
	v_mul_f32_e32 v131, v127, v127
	v_mul_f32_e32 v132, v128, v128
	v_mul_f32_e32 v133, v129, v129
	v_mul_f32_e32 v134, v122, v122
	v_mul_f32_e32 v135, v123, v123
	v_mul_f32_e32 v136, v124, v124
	v_mul_f32_e32 v137, v125, v125
	v_fmamk_f32 v130, v130, 0xbdd2d3e7, v138
	v_fmamk_f32 v131, v131, 0xbdd2d3e7, v138
	v_fmamk_f32 v132, v132, 0xbdd2d3e7, v138
	v_fmamk_f32 v133, v133, 0xbdd2d3e7, v138
	v_fmamk_f32 v134, v134, 0xbdd2d3e7, v138
	v_fmamk_f32 v135, v135, 0xbdd2d3e7, v138
	v_fmamk_f32 v136, v136, 0xbdd2d3e7, v138
	v_fmamk_f32 v137, v137, 0xbdd2d3e7, v138
	v_mul_f32_e32 v130, v126, v130
	v_mul_f32_e32 v131, v127, v131
	v_mul_f32_e32 v132, v128, v132
	v_mul_f32_e32 v133, v129, v133
	v_mul_f32_e32 v134, v122, v134
	v_mul_f32_e32 v135, v123, v135
	v_mul_f32_e32 v136, v124, v136
	v_mul_f32_e32 v137, v125, v137
	v_exp_f32_e32 v130, v130
	v_exp_f32_e32 v131, v131
	v_exp_f32_e32 v132, v132
	v_exp_f32_e32 v133, v133
	v_exp_f32_e32 v134, v134
	v_exp_f32_e32 v135, v135
	v_exp_f32_e32 v136, v136
	v_exp_f32_e32 v137, v137
	v_add_f32_e32 v130, 1.0, v130
	v_add_f32_e32 v131, 1.0, v131
	v_add_f32_e32 v132, 1.0, v132
	v_add_f32_e32 v133, 1.0, v133
	v_add_f32_e32 v134, 1.0, v134
	v_add_f32_e32 v135, 1.0, v135
	v_add_f32_e32 v136, 1.0, v136
	v_add_f32_e32 v137, 1.0, v137
	v_rcp_f32_e32 v130, v130
	v_rcp_f32_e32 v131, v131
	v_rcp_f32_e32 v132, v132
	v_rcp_f32_e32 v133, v133
	v_rcp_f32_e32 v134, v134
	v_rcp_f32_e32 v135, v135
	v_rcp_f32_e32 v136, v136
	v_rcp_f32_e32 v137, v137
	v_mul_f32_e32 v126, v126, v130
	v_mul_f32_e32 v127, v127, v131
	v_mul_f32_e32 v128, v128, v132
	v_mul_f32_e32 v129, v129, v133
	v_mul_f32_e32 v122, v122, v134
	v_mul_f32_e32 v123, v123, v135
	v_mul_f32_e32 v124, v124, v136
	v_mul_f32_e32 v125, v125, v137
	v_cvt_pk_bf16_f32 v126, v126, v127
	v_cvt_pk_bf16_f32 v127, v128, v129
	v_cvt_pk_bf16_f32 v128, v122, v123
	v_cvt_pk_bf16_f32 v129, v124, v125
	global_store_dwordx4 v139, v[126:129], s[66:67] offset:-4096
	v_mul_f32_e32 v130, v118, v118
	v_mul_f32_e32 v131, v119, v119
	v_mul_f32_e32 v132, v120, v120
	v_mul_f32_e32 v133, v121, v121
	v_mul_f32_e32 v134, v114, v114
	v_mul_f32_e32 v135, v115, v115
	v_mul_f32_e32 v136, v116, v116
	v_mul_f32_e32 v137, v117, v117
	v_fmamk_f32 v130, v130, 0xbdd2d3e7, v138
	v_fmamk_f32 v131, v131, 0xbdd2d3e7, v138
	v_fmamk_f32 v132, v132, 0xbdd2d3e7, v138
	v_fmamk_f32 v133, v133, 0xbdd2d3e7, v138
	v_fmamk_f32 v134, v134, 0xbdd2d3e7, v138
	v_fmamk_f32 v135, v135, 0xbdd2d3e7, v138
	v_fmamk_f32 v136, v136, 0xbdd2d3e7, v138
	v_fmamk_f32 v137, v137, 0xbdd2d3e7, v138
	v_mul_f32_e32 v130, v118, v130
	v_mul_f32_e32 v131, v119, v131
	v_mul_f32_e32 v132, v120, v132
	v_mul_f32_e32 v133, v121, v133
	v_mul_f32_e32 v134, v114, v134
	v_mul_f32_e32 v135, v115, v135
	v_mul_f32_e32 v136, v116, v136
	v_mul_f32_e32 v137, v117, v137
	v_exp_f32_e32 v130, v130
	v_exp_f32_e32 v131, v131
	v_exp_f32_e32 v132, v132
	v_exp_f32_e32 v133, v133
	v_exp_f32_e32 v134, v134
	v_exp_f32_e32 v135, v135
	v_exp_f32_e32 v136, v136
	v_exp_f32_e32 v137, v137
	v_add_f32_e32 v130, 1.0, v130
	v_add_f32_e32 v131, 1.0, v131
	v_add_f32_e32 v132, 1.0, v132
	v_add_f32_e32 v133, 1.0, v133
	v_add_f32_e32 v134, 1.0, v134
	v_add_f32_e32 v135, 1.0, v135
	v_add_f32_e32 v136, 1.0, v136
	v_add_f32_e32 v137, 1.0, v137
	v_rcp_f32_e32 v130, v130
	v_rcp_f32_e32 v131, v131
	v_rcp_f32_e32 v132, v132
	v_rcp_f32_e32 v133, v133
	v_rcp_f32_e32 v134, v134
	v_rcp_f32_e32 v135, v135
	v_rcp_f32_e32 v136, v136
	v_rcp_f32_e32 v137, v137
	v_mul_f32_e32 v118, v118, v130
	v_mul_f32_e32 v119, v119, v131
	v_mul_f32_e32 v120, v120, v132
	v_mul_f32_e32 v121, v121, v133
	v_mul_f32_e32 v114, v114, v134
	v_mul_f32_e32 v115, v115, v135
	v_mul_f32_e32 v116, v116, v136
	v_mul_f32_e32 v117, v117, v137
	v_cvt_pk_bf16_f32 v118, v118, v119
	v_cvt_pk_bf16_f32 v119, v120, v121
	v_cvt_pk_bf16_f32 v120, v114, v115
	v_cvt_pk_bf16_f32 v121, v116, v117
	global_store_dwordx4 v139, v[118:121], s[66:67]
	s_add_u32 s66, s66, 0x4000
	s_addc_u32 s67, s67, 0
	v_mul_f32_e32 v130, v110, v110
	v_mul_f32_e32 v131, v111, v111
	v_mul_f32_e32 v132, v112, v112
	v_mul_f32_e32 v133, v113, v113
	v_mul_f32_e32 v134, v106, v106
	v_mul_f32_e32 v135, v107, v107
	v_mul_f32_e32 v136, v108, v108
	v_mul_f32_e32 v137, v109, v109
	v_fmamk_f32 v130, v130, 0xbdd2d3e7, v138
	v_fmamk_f32 v131, v131, 0xbdd2d3e7, v138
	v_fmamk_f32 v132, v132, 0xbdd2d3e7, v138
	v_fmamk_f32 v133, v133, 0xbdd2d3e7, v138
	v_fmamk_f32 v134, v134, 0xbdd2d3e7, v138
	v_fmamk_f32 v135, v135, 0xbdd2d3e7, v138
	v_fmamk_f32 v136, v136, 0xbdd2d3e7, v138
	v_fmamk_f32 v137, v137, 0xbdd2d3e7, v138
	v_mul_f32_e32 v130, v110, v130
	v_mul_f32_e32 v131, v111, v131
	v_mul_f32_e32 v132, v112, v132
	v_mul_f32_e32 v133, v113, v133
	v_mul_f32_e32 v134, v106, v134
	v_mul_f32_e32 v135, v107, v135
	v_mul_f32_e32 v136, v108, v136
	v_mul_f32_e32 v137, v109, v137
	v_exp_f32_e32 v130, v130
	v_exp_f32_e32 v131, v131
	v_exp_f32_e32 v132, v132
	v_exp_f32_e32 v133, v133
	v_exp_f32_e32 v134, v134
	v_exp_f32_e32 v135, v135
	v_exp_f32_e32 v136, v136
	v_exp_f32_e32 v137, v137
	v_add_f32_e32 v130, 1.0, v130
	v_add_f32_e32 v131, 1.0, v131
	v_add_f32_e32 v132, 1.0, v132
	v_add_f32_e32 v133, 1.0, v133
	v_add_f32_e32 v134, 1.0, v134
	v_add_f32_e32 v135, 1.0, v135
	v_add_f32_e32 v136, 1.0, v136
	v_add_f32_e32 v137, 1.0, v137
	v_rcp_f32_e32 v130, v130
	v_rcp_f32_e32 v131, v131
	v_rcp_f32_e32 v132, v132
	v_rcp_f32_e32 v133, v133
	v_rcp_f32_e32 v134, v134
	v_rcp_f32_e32 v135, v135
	v_rcp_f32_e32 v136, v136
	v_rcp_f32_e32 v137, v137
	v_mul_f32_e32 v110, v110, v130
	v_mul_f32_e32 v111, v111, v131
	v_mul_f32_e32 v112, v112, v132
	v_mul_f32_e32 v113, v113, v133
	v_mul_f32_e32 v106, v106, v134
	v_mul_f32_e32 v107, v107, v135
	v_mul_f32_e32 v108, v108, v136
	v_mul_f32_e32 v109, v109, v137
	v_cvt_pk_bf16_f32 v110, v110, v111
	v_cvt_pk_bf16_f32 v111, v112, v113
	v_cvt_pk_bf16_f32 v112, v106, v107
	v_cvt_pk_bf16_f32 v113, v108, v109
	global_store_dwordx4 v139, v[110:113], s[66:67] offset:-4096
	v_mul_f32_e32 v130, v102, v102
	v_mul_f32_e32 v131, v103, v103
	v_mul_f32_e32 v132, v104, v104
	v_mul_f32_e32 v133, v105, v105
	v_mul_f32_e32 v134, v98, v98
	v_mul_f32_e32 v135, v99, v99
	v_mul_f32_e32 v136, v100, v100
	v_mul_f32_e32 v137, v101, v101
	v_fmamk_f32 v130, v130, 0xbdd2d3e7, v138
	v_fmamk_f32 v131, v131, 0xbdd2d3e7, v138
	v_fmamk_f32 v132, v132, 0xbdd2d3e7, v138
	v_fmamk_f32 v133, v133, 0xbdd2d3e7, v138
	v_fmamk_f32 v134, v134, 0xbdd2d3e7, v138
	v_fmamk_f32 v135, v135, 0xbdd2d3e7, v138
	v_fmamk_f32 v136, v136, 0xbdd2d3e7, v138
	v_fmamk_f32 v137, v137, 0xbdd2d3e7, v138
	v_mul_f32_e32 v130, v102, v130
	v_mul_f32_e32 v131, v103, v131
	v_mul_f32_e32 v132, v104, v132
	v_mul_f32_e32 v133, v105, v133
	v_mul_f32_e32 v134, v98, v134
	v_mul_f32_e32 v135, v99, v135
	v_mul_f32_e32 v136, v100, v136
	v_mul_f32_e32 v137, v101, v137
	v_exp_f32_e32 v130, v130
	v_exp_f32_e32 v131, v131
	v_exp_f32_e32 v132, v132
	v_exp_f32_e32 v133, v133
	v_exp_f32_e32 v134, v134
	v_exp_f32_e32 v135, v135
	v_exp_f32_e32 v136, v136
	v_exp_f32_e32 v137, v137
	v_add_f32_e32 v130, 1.0, v130
	v_add_f32_e32 v131, 1.0, v131
	v_add_f32_e32 v132, 1.0, v132
	v_add_f32_e32 v133, 1.0, v133
	v_add_f32_e32 v134, 1.0, v134
	v_add_f32_e32 v135, 1.0, v135
	v_add_f32_e32 v136, 1.0, v136
	v_add_f32_e32 v137, 1.0, v137
	v_rcp_f32_e32 v130, v130
	v_rcp_f32_e32 v131, v131
	v_rcp_f32_e32 v132, v132
	v_rcp_f32_e32 v133, v133
	v_rcp_f32_e32 v134, v134
	v_rcp_f32_e32 v135, v135
	v_rcp_f32_e32 v136, v136
	v_rcp_f32_e32 v137, v137
	v_mul_f32_e32 v102, v102, v130
	v_mul_f32_e32 v103, v103, v131
	v_mul_f32_e32 v104, v104, v132
	v_mul_f32_e32 v105, v105, v133
	v_mul_f32_e32 v98, v98, v134
	v_mul_f32_e32 v99, v99, v135
	v_mul_f32_e32 v100, v100, v136
	v_mul_f32_e32 v101, v101, v137
	v_cvt_pk_bf16_f32 v102, v102, v103
	v_cvt_pk_bf16_f32 v103, v104, v105
	v_cvt_pk_bf16_f32 v104, v98, v99
	v_cvt_pk_bf16_f32 v105, v100, v101
	global_store_dwordx4 v139, v[102:105], s[66:67]
	s_add_u32 s66, s66, 0x4000
	s_addc_u32 s67, s67, 0
	v_mul_f32_e32 v130, v94, v94
	v_mul_f32_e32 v131, v95, v95
	v_mul_f32_e32 v132, v96, v96
	v_mul_f32_e32 v133, v97, v97
	v_mul_f32_e32 v134, v90, v90
	v_mul_f32_e32 v135, v91, v91
	v_mul_f32_e32 v136, v92, v92
	v_mul_f32_e32 v137, v93, v93
	v_fmamk_f32 v130, v130, 0xbdd2d3e7, v138
	v_fmamk_f32 v131, v131, 0xbdd2d3e7, v138
	v_fmamk_f32 v132, v132, 0xbdd2d3e7, v138
	v_fmamk_f32 v133, v133, 0xbdd2d3e7, v138
	v_fmamk_f32 v134, v134, 0xbdd2d3e7, v138
	v_fmamk_f32 v135, v135, 0xbdd2d3e7, v138
	v_fmamk_f32 v136, v136, 0xbdd2d3e7, v138
	v_fmamk_f32 v137, v137, 0xbdd2d3e7, v138
	v_mul_f32_e32 v130, v94, v130
	v_mul_f32_e32 v131, v95, v131
	v_mul_f32_e32 v132, v96, v132
	v_mul_f32_e32 v133, v97, v133
	v_mul_f32_e32 v134, v90, v134
	v_mul_f32_e32 v135, v91, v135
	v_mul_f32_e32 v136, v92, v136
	v_mul_f32_e32 v137, v93, v137
	v_exp_f32_e32 v130, v130
	v_exp_f32_e32 v131, v131
	v_exp_f32_e32 v132, v132
	v_exp_f32_e32 v133, v133
	v_exp_f32_e32 v134, v134
	v_exp_f32_e32 v135, v135
	v_exp_f32_e32 v136, v136
	v_exp_f32_e32 v137, v137
	v_add_f32_e32 v130, 1.0, v130
	v_add_f32_e32 v131, 1.0, v131
	v_add_f32_e32 v132, 1.0, v132
	v_add_f32_e32 v133, 1.0, v133
	v_add_f32_e32 v134, 1.0, v134
	v_add_f32_e32 v135, 1.0, v135
	v_add_f32_e32 v136, 1.0, v136
	v_add_f32_e32 v137, 1.0, v137
	v_rcp_f32_e32 v130, v130
	v_rcp_f32_e32 v131, v131
	v_rcp_f32_e32 v132, v132
	v_rcp_f32_e32 v133, v133
	v_rcp_f32_e32 v134, v134
	v_rcp_f32_e32 v135, v135
	v_rcp_f32_e32 v136, v136
	v_rcp_f32_e32 v137, v137
	v_mul_f32_e32 v94, v94, v130
	v_mul_f32_e32 v95, v95, v131
	v_mul_f32_e32 v96, v96, v132
	v_mul_f32_e32 v97, v97, v133
	v_mul_f32_e32 v90, v90, v134
	v_mul_f32_e32 v91, v91, v135
	v_mul_f32_e32 v92, v92, v136
	v_mul_f32_e32 v93, v93, v137
	v_cvt_pk_bf16_f32 v94, v94, v95
	v_cvt_pk_bf16_f32 v95, v96, v97
	v_cvt_pk_bf16_f32 v96, v90, v91
	v_cvt_pk_bf16_f32 v97, v92, v93
	global_store_dwordx4 v139, v[94:97], s[66:67] offset:-4096
	v_mul_f32_e32 v130, v86, v86
	v_mul_f32_e32 v131, v87, v87
	v_mul_f32_e32 v132, v88, v88
	v_mul_f32_e32 v133, v89, v89
	v_mul_f32_e32 v134, v82, v82
	v_mul_f32_e32 v135, v83, v83
	v_mul_f32_e32 v136, v84, v84
	v_mul_f32_e32 v137, v85, v85
	v_fmamk_f32 v130, v130, 0xbdd2d3e7, v138
	v_fmamk_f32 v131, v131, 0xbdd2d3e7, v138
	v_fmamk_f32 v132, v132, 0xbdd2d3e7, v138
	v_fmamk_f32 v133, v133, 0xbdd2d3e7, v138
	v_fmamk_f32 v134, v134, 0xbdd2d3e7, v138
	v_fmamk_f32 v135, v135, 0xbdd2d3e7, v138
	v_fmamk_f32 v136, v136, 0xbdd2d3e7, v138
	v_fmamk_f32 v137, v137, 0xbdd2d3e7, v138
	v_mul_f32_e32 v130, v86, v130
	v_mul_f32_e32 v131, v87, v131
	v_mul_f32_e32 v132, v88, v132
	v_mul_f32_e32 v133, v89, v133
	v_mul_f32_e32 v134, v82, v134
	v_mul_f32_e32 v135, v83, v135
	v_mul_f32_e32 v136, v84, v136
	v_mul_f32_e32 v137, v85, v137
	v_exp_f32_e32 v130, v130
	v_exp_f32_e32 v131, v131
	v_exp_f32_e32 v132, v132
	v_exp_f32_e32 v133, v133
	v_exp_f32_e32 v134, v134
	v_exp_f32_e32 v135, v135
	v_exp_f32_e32 v136, v136
	v_exp_f32_e32 v137, v137
	v_add_f32_e32 v130, 1.0, v130
	v_add_f32_e32 v131, 1.0, v131
	v_add_f32_e32 v132, 1.0, v132
	v_add_f32_e32 v133, 1.0, v133
	v_add_f32_e32 v134, 1.0, v134
	v_add_f32_e32 v135, 1.0, v135
	v_add_f32_e32 v136, 1.0, v136
	v_add_f32_e32 v137, 1.0, v137
	v_rcp_f32_e32 v130, v130
	v_rcp_f32_e32 v131, v131
	v_rcp_f32_e32 v132, v132
	v_rcp_f32_e32 v133, v133
	v_rcp_f32_e32 v134, v134
	v_rcp_f32_e32 v135, v135
	v_rcp_f32_e32 v136, v136
	v_rcp_f32_e32 v137, v137
	v_mul_f32_e32 v86, v86, v130
	v_mul_f32_e32 v87, v87, v131
	v_mul_f32_e32 v88, v88, v132
	v_mul_f32_e32 v89, v89, v133
	v_mul_f32_e32 v82, v82, v134
	v_mul_f32_e32 v83, v83, v135
	v_mul_f32_e32 v84, v84, v136
	v_mul_f32_e32 v85, v85, v137
	v_cvt_pk_bf16_f32 v86, v86, v87
	v_cvt_pk_bf16_f32 v87, v88, v89
	v_cvt_pk_bf16_f32 v88, v82, v83
	v_cvt_pk_bf16_f32 v89, v84, v85
	global_store_dwordx4 v139, v[86:89], s[66:67]
	s_add_u32 s66, s66, 0x4000
	s_addc_u32 s67, s67, 0
	v_mul_f32_e32 v130, v78, v78
	v_mul_f32_e32 v131, v79, v79
	v_mul_f32_e32 v132, v80, v80
	v_mul_f32_e32 v133, v81, v81
	v_mul_f32_e32 v134, v74, v74
	v_mul_f32_e32 v135, v75, v75
	v_mul_f32_e32 v136, v76, v76
	v_mul_f32_e32 v137, v77, v77
	v_fmamk_f32 v130, v130, 0xbdd2d3e7, v138
	v_fmamk_f32 v131, v131, 0xbdd2d3e7, v138
	v_fmamk_f32 v132, v132, 0xbdd2d3e7, v138
	v_fmamk_f32 v133, v133, 0xbdd2d3e7, v138
	v_fmamk_f32 v134, v134, 0xbdd2d3e7, v138
	v_fmamk_f32 v135, v135, 0xbdd2d3e7, v138
	v_fmamk_f32 v136, v136, 0xbdd2d3e7, v138
	v_fmamk_f32 v137, v137, 0xbdd2d3e7, v138
	v_mul_f32_e32 v130, v78, v130
	v_mul_f32_e32 v131, v79, v131
	v_mul_f32_e32 v132, v80, v132
	v_mul_f32_e32 v133, v81, v133
	v_mul_f32_e32 v134, v74, v134
	v_mul_f32_e32 v135, v75, v135
	v_mul_f32_e32 v136, v76, v136
	v_mul_f32_e32 v137, v77, v137
	v_exp_f32_e32 v130, v130
	v_exp_f32_e32 v131, v131
	v_exp_f32_e32 v132, v132
	v_exp_f32_e32 v133, v133
	v_exp_f32_e32 v134, v134
	v_exp_f32_e32 v135, v135
	v_exp_f32_e32 v136, v136
	v_exp_f32_e32 v137, v137
	v_add_f32_e32 v130, 1.0, v130
	v_add_f32_e32 v131, 1.0, v131
	v_add_f32_e32 v132, 1.0, v132
	v_add_f32_e32 v133, 1.0, v133
	v_add_f32_e32 v134, 1.0, v134
	v_add_f32_e32 v135, 1.0, v135
	v_add_f32_e32 v136, 1.0, v136
	v_add_f32_e32 v137, 1.0, v137
	v_rcp_f32_e32 v130, v130
	v_rcp_f32_e32 v131, v131
	v_rcp_f32_e32 v132, v132
	v_rcp_f32_e32 v133, v133
	v_rcp_f32_e32 v134, v134
	v_rcp_f32_e32 v135, v135
	v_rcp_f32_e32 v136, v136
	v_rcp_f32_e32 v137, v137
	v_mul_f32_e32 v78, v78, v130
	v_mul_f32_e32 v79, v79, v131
	v_mul_f32_e32 v80, v80, v132
	v_mul_f32_e32 v81, v81, v133
	v_mul_f32_e32 v74, v74, v134
	v_mul_f32_e32 v75, v75, v135
	v_mul_f32_e32 v76, v76, v136
	v_mul_f32_e32 v77, v77, v137
	v_cvt_pk_bf16_f32 v78, v78, v79
	v_cvt_pk_bf16_f32 v79, v80, v81
	v_cvt_pk_bf16_f32 v80, v74, v75
	v_cvt_pk_bf16_f32 v81, v76, v77
	global_store_dwordx4 v139, v[78:81], s[66:67] offset:-4096
	v_mul_f32_e32 v130, v70, v70
	v_mul_f32_e32 v131, v71, v71
	v_mul_f32_e32 v132, v72, v72
	v_mul_f32_e32 v133, v73, v73
	v_mul_f32_e32 v134, v66, v66
	v_mul_f32_e32 v135, v67, v67
	v_mul_f32_e32 v136, v68, v68
	v_mul_f32_e32 v137, v69, v69
	v_fmamk_f32 v130, v130, 0xbdd2d3e7, v138
	v_fmamk_f32 v131, v131, 0xbdd2d3e7, v138
	v_fmamk_f32 v132, v132, 0xbdd2d3e7, v138
	v_fmamk_f32 v133, v133, 0xbdd2d3e7, v138
	v_fmamk_f32 v134, v134, 0xbdd2d3e7, v138
	v_fmamk_f32 v135, v135, 0xbdd2d3e7, v138
	v_fmamk_f32 v136, v136, 0xbdd2d3e7, v138
	v_fmamk_f32 v137, v137, 0xbdd2d3e7, v138
	v_mul_f32_e32 v130, v70, v130
	v_mul_f32_e32 v131, v71, v131
	v_mul_f32_e32 v132, v72, v132
	v_mul_f32_e32 v133, v73, v133
	v_mul_f32_e32 v134, v66, v134
	v_mul_f32_e32 v135, v67, v135
	v_mul_f32_e32 v136, v68, v136
	v_mul_f32_e32 v137, v69, v137
	v_exp_f32_e32 v130, v130
	v_exp_f32_e32 v131, v131
	v_exp_f32_e32 v132, v132
	v_exp_f32_e32 v133, v133
	v_exp_f32_e32 v134, v134
	v_exp_f32_e32 v135, v135
	v_exp_f32_e32 v136, v136
	v_exp_f32_e32 v137, v137
	v_add_f32_e32 v130, 1.0, v130
	v_add_f32_e32 v131, 1.0, v131
	v_add_f32_e32 v132, 1.0, v132
	v_add_f32_e32 v133, 1.0, v133
	v_add_f32_e32 v134, 1.0, v134
	v_add_f32_e32 v135, 1.0, v135
	v_add_f32_e32 v136, 1.0, v136
	v_add_f32_e32 v137, 1.0, v137
	v_rcp_f32_e32 v130, v130
	v_rcp_f32_e32 v131, v131
	v_rcp_f32_e32 v132, v132
	v_rcp_f32_e32 v133, v133
	v_rcp_f32_e32 v134, v134
	v_rcp_f32_e32 v135, v135
	v_rcp_f32_e32 v136, v136
	v_rcp_f32_e32 v137, v137
	v_mul_f32_e32 v70, v70, v130
	v_mul_f32_e32 v71, v71, v131
	v_mul_f32_e32 v72, v72, v132
	v_mul_f32_e32 v73, v73, v133
	v_mul_f32_e32 v66, v66, v134
	v_mul_f32_e32 v67, v67, v135
	v_mul_f32_e32 v68, v68, v136
	v_mul_f32_e32 v69, v69, v137
	v_cvt_pk_bf16_f32 v70, v70, v71
	v_cvt_pk_bf16_f32 v71, v72, v73
	v_cvt_pk_bf16_f32 v72, v66, v67
	v_cvt_pk_bf16_f32 v73, v68, v69
	global_store_dwordx4 v139, v[70:73], s[66:67]
	s_add_u32 s66, s66, 0x14000
	s_addc_u32 s67, s67, 0
	v_mul_f32_e32 v130, v62, v62
	v_mul_f32_e32 v131, v63, v63
	v_mul_f32_e32 v132, v64, v64
	v_mul_f32_e32 v133, v65, v65
	v_mul_f32_e32 v134, v58, v58
	v_mul_f32_e32 v135, v59, v59
	v_mul_f32_e32 v136, v60, v60
	v_mul_f32_e32 v137, v61, v61
	v_fmamk_f32 v130, v130, 0xbdd2d3e7, v138
	v_fmamk_f32 v131, v131, 0xbdd2d3e7, v138
	v_fmamk_f32 v132, v132, 0xbdd2d3e7, v138
	v_fmamk_f32 v133, v133, 0xbdd2d3e7, v138
	v_fmamk_f32 v134, v134, 0xbdd2d3e7, v138
	v_fmamk_f32 v135, v135, 0xbdd2d3e7, v138
	v_fmamk_f32 v136, v136, 0xbdd2d3e7, v138
	v_fmamk_f32 v137, v137, 0xbdd2d3e7, v138
	v_mul_f32_e32 v130, v62, v130
	v_mul_f32_e32 v131, v63, v131
	v_mul_f32_e32 v132, v64, v132
	v_mul_f32_e32 v133, v65, v133
	v_mul_f32_e32 v134, v58, v134
	v_mul_f32_e32 v135, v59, v135
	v_mul_f32_e32 v136, v60, v136
	v_mul_f32_e32 v137, v61, v137
	v_exp_f32_e32 v130, v130
	v_exp_f32_e32 v131, v131
	v_exp_f32_e32 v132, v132
	v_exp_f32_e32 v133, v133
	v_exp_f32_e32 v134, v134
	v_exp_f32_e32 v135, v135
	v_exp_f32_e32 v136, v136
	v_exp_f32_e32 v137, v137
	v_add_f32_e32 v130, 1.0, v130
	v_add_f32_e32 v131, 1.0, v131
	v_add_f32_e32 v132, 1.0, v132
	v_add_f32_e32 v133, 1.0, v133
	v_add_f32_e32 v134, 1.0, v134
	v_add_f32_e32 v135, 1.0, v135
	v_add_f32_e32 v136, 1.0, v136
	v_add_f32_e32 v137, 1.0, v137
	v_rcp_f32_e32 v130, v130
	v_rcp_f32_e32 v131, v131
	v_rcp_f32_e32 v132, v132
	v_rcp_f32_e32 v133, v133
	v_rcp_f32_e32 v134, v134
	v_rcp_f32_e32 v135, v135
	v_rcp_f32_e32 v136, v136
	v_rcp_f32_e32 v137, v137
	v_mul_f32_e32 v62, v62, v130
	v_mul_f32_e32 v63, v63, v131
	v_mul_f32_e32 v64, v64, v132
	v_mul_f32_e32 v65, v65, v133
	v_mul_f32_e32 v58, v58, v134
	v_mul_f32_e32 v59, v59, v135
	v_mul_f32_e32 v60, v60, v136
	v_mul_f32_e32 v61, v61, v137
	v_cvt_pk_bf16_f32 v62, v62, v63
	v_cvt_pk_bf16_f32 v63, v64, v65
	v_cvt_pk_bf16_f32 v64, v58, v59
	v_cvt_pk_bf16_f32 v65, v60, v61
	global_store_dwordx4 v139, v[62:65], s[66:67] offset:-4096
	v_mul_f32_e32 v130, v54, v54
	v_mul_f32_e32 v131, v55, v55
	v_mul_f32_e32 v132, v56, v56
	v_mul_f32_e32 v133, v57, v57
	v_mul_f32_e32 v134, v50, v50
	v_mul_f32_e32 v135, v51, v51
	v_mul_f32_e32 v136, v52, v52
	v_mul_f32_e32 v137, v53, v53
	v_fmamk_f32 v130, v130, 0xbdd2d3e7, v138
	v_fmamk_f32 v131, v131, 0xbdd2d3e7, v138
	v_fmamk_f32 v132, v132, 0xbdd2d3e7, v138
	v_fmamk_f32 v133, v133, 0xbdd2d3e7, v138
	v_fmamk_f32 v134, v134, 0xbdd2d3e7, v138
	v_fmamk_f32 v135, v135, 0xbdd2d3e7, v138
	v_fmamk_f32 v136, v136, 0xbdd2d3e7, v138
	v_fmamk_f32 v137, v137, 0xbdd2d3e7, v138
	v_mul_f32_e32 v130, v54, v130
	v_mul_f32_e32 v131, v55, v131
	v_mul_f32_e32 v132, v56, v132
	v_mul_f32_e32 v133, v57, v133
	v_mul_f32_e32 v134, v50, v134
	v_mul_f32_e32 v135, v51, v135
	v_mul_f32_e32 v136, v52, v136
	v_mul_f32_e32 v137, v53, v137
	v_exp_f32_e32 v130, v130
	v_exp_f32_e32 v131, v131
	v_exp_f32_e32 v132, v132
	v_exp_f32_e32 v133, v133
	v_exp_f32_e32 v134, v134
	v_exp_f32_e32 v135, v135
	v_exp_f32_e32 v136, v136
	v_exp_f32_e32 v137, v137
	v_add_f32_e32 v130, 1.0, v130
	v_add_f32_e32 v131, 1.0, v131
	v_add_f32_e32 v132, 1.0, v132
	v_add_f32_e32 v133, 1.0, v133
	v_add_f32_e32 v134, 1.0, v134
	v_add_f32_e32 v135, 1.0, v135
	v_add_f32_e32 v136, 1.0, v136
	v_add_f32_e32 v137, 1.0, v137
	v_rcp_f32_e32 v130, v130
	v_rcp_f32_e32 v131, v131
	v_rcp_f32_e32 v132, v132
	v_rcp_f32_e32 v133, v133
	v_rcp_f32_e32 v134, v134
	v_rcp_f32_e32 v135, v135
	v_rcp_f32_e32 v136, v136
	v_rcp_f32_e32 v137, v137
	v_mul_f32_e32 v54, v54, v130
	v_mul_f32_e32 v55, v55, v131
	v_mul_f32_e32 v56, v56, v132
	v_mul_f32_e32 v57, v57, v133
	v_mul_f32_e32 v50, v50, v134
	v_mul_f32_e32 v51, v51, v135
	v_mul_f32_e32 v52, v52, v136
	v_mul_f32_e32 v53, v53, v137
	v_cvt_pk_bf16_f32 v54, v54, v55
	v_cvt_pk_bf16_f32 v55, v56, v57
	v_cvt_pk_bf16_f32 v56, v50, v51
	v_cvt_pk_bf16_f32 v57, v52, v53
	global_store_dwordx4 v139, v[54:57], s[66:67]
	s_add_u32 s66, s66, 0x4000
	s_addc_u32 s67, s67, 0
	v_mul_f32_e32 v130, v46, v46
	v_mul_f32_e32 v131, v47, v47
	v_mul_f32_e32 v132, v48, v48
	v_mul_f32_e32 v133, v49, v49
	v_mul_f32_e32 v134, v42, v42
	v_mul_f32_e32 v135, v43, v43
	v_mul_f32_e32 v136, v44, v44
	v_mul_f32_e32 v137, v45, v45
	v_fmamk_f32 v130, v130, 0xbdd2d3e7, v138
	v_fmamk_f32 v131, v131, 0xbdd2d3e7, v138
	v_fmamk_f32 v132, v132, 0xbdd2d3e7, v138
	v_fmamk_f32 v133, v133, 0xbdd2d3e7, v138
	v_fmamk_f32 v134, v134, 0xbdd2d3e7, v138
	v_fmamk_f32 v135, v135, 0xbdd2d3e7, v138
	v_fmamk_f32 v136, v136, 0xbdd2d3e7, v138
	v_fmamk_f32 v137, v137, 0xbdd2d3e7, v138
	v_mul_f32_e32 v130, v46, v130
	v_mul_f32_e32 v131, v47, v131
	v_mul_f32_e32 v132, v48, v132
	v_mul_f32_e32 v133, v49, v133
	v_mul_f32_e32 v134, v42, v134
	v_mul_f32_e32 v135, v43, v135
	v_mul_f32_e32 v136, v44, v136
	v_mul_f32_e32 v137, v45, v137
	v_exp_f32_e32 v130, v130
	v_exp_f32_e32 v131, v131
	v_exp_f32_e32 v132, v132
	v_exp_f32_e32 v133, v133
	v_exp_f32_e32 v134, v134
	v_exp_f32_e32 v135, v135
	v_exp_f32_e32 v136, v136
	v_exp_f32_e32 v137, v137
	v_add_f32_e32 v130, 1.0, v130
	v_add_f32_e32 v131, 1.0, v131
	v_add_f32_e32 v132, 1.0, v132
	v_add_f32_e32 v133, 1.0, v133
	v_add_f32_e32 v134, 1.0, v134
	v_add_f32_e32 v135, 1.0, v135
	v_add_f32_e32 v136, 1.0, v136
	v_add_f32_e32 v137, 1.0, v137
	v_rcp_f32_e32 v130, v130
	v_rcp_f32_e32 v131, v131
	v_rcp_f32_e32 v132, v132
	v_rcp_f32_e32 v133, v133
	v_rcp_f32_e32 v134, v134
	v_rcp_f32_e32 v135, v135
	v_rcp_f32_e32 v136, v136
	v_rcp_f32_e32 v137, v137
	v_mul_f32_e32 v46, v46, v130
	v_mul_f32_e32 v47, v47, v131
	v_mul_f32_e32 v48, v48, v132
	v_mul_f32_e32 v49, v49, v133
	v_mul_f32_e32 v42, v42, v134
	v_mul_f32_e32 v43, v43, v135
	v_mul_f32_e32 v44, v44, v136
	v_mul_f32_e32 v45, v45, v137
	v_cvt_pk_bf16_f32 v46, v46, v47
	v_cvt_pk_bf16_f32 v47, v48, v49
	v_cvt_pk_bf16_f32 v48, v42, v43
	v_cvt_pk_bf16_f32 v49, v44, v45
	global_store_dwordx4 v139, v[46:49], s[66:67] offset:-4096
	v_mul_f32_e32 v130, v38, v38
	v_mul_f32_e32 v131, v39, v39
	v_mul_f32_e32 v132, v40, v40
	v_mul_f32_e32 v133, v41, v41
	v_mul_f32_e32 v134, v34, v34
	v_mul_f32_e32 v135, v35, v35
	v_mul_f32_e32 v136, v36, v36
	v_mul_f32_e32 v137, v37, v37
	v_fmamk_f32 v130, v130, 0xbdd2d3e7, v138
	v_fmamk_f32 v131, v131, 0xbdd2d3e7, v138
	v_fmamk_f32 v132, v132, 0xbdd2d3e7, v138
	v_fmamk_f32 v133, v133, 0xbdd2d3e7, v138
	v_fmamk_f32 v134, v134, 0xbdd2d3e7, v138
	v_fmamk_f32 v135, v135, 0xbdd2d3e7, v138
	v_fmamk_f32 v136, v136, 0xbdd2d3e7, v138
	v_fmamk_f32 v137, v137, 0xbdd2d3e7, v138
	v_mul_f32_e32 v130, v38, v130
	v_mul_f32_e32 v131, v39, v131
	v_mul_f32_e32 v132, v40, v132
	v_mul_f32_e32 v133, v41, v133
	v_mul_f32_e32 v134, v34, v134
	v_mul_f32_e32 v135, v35, v135
	v_mul_f32_e32 v136, v36, v136
	v_mul_f32_e32 v137, v37, v137
	v_exp_f32_e32 v130, v130
	v_exp_f32_e32 v131, v131
	v_exp_f32_e32 v132, v132
	v_exp_f32_e32 v133, v133
	v_exp_f32_e32 v134, v134
	v_exp_f32_e32 v135, v135
	v_exp_f32_e32 v136, v136
	v_exp_f32_e32 v137, v137
	v_add_f32_e32 v130, 1.0, v130
	v_add_f32_e32 v131, 1.0, v131
	v_add_f32_e32 v132, 1.0, v132
	v_add_f32_e32 v133, 1.0, v133
	v_add_f32_e32 v134, 1.0, v134
	v_add_f32_e32 v135, 1.0, v135
	v_add_f32_e32 v136, 1.0, v136
	v_add_f32_e32 v137, 1.0, v137
	v_rcp_f32_e32 v130, v130
	v_rcp_f32_e32 v131, v131
	v_rcp_f32_e32 v132, v132
	v_rcp_f32_e32 v133, v133
	v_rcp_f32_e32 v134, v134
	v_rcp_f32_e32 v135, v135
	v_rcp_f32_e32 v136, v136
	v_rcp_f32_e32 v137, v137
	v_mul_f32_e32 v38, v38, v130
	v_mul_f32_e32 v39, v39, v131
	v_mul_f32_e32 v40, v40, v132
	v_mul_f32_e32 v41, v41, v133
	v_mul_f32_e32 v34, v34, v134
	v_mul_f32_e32 v35, v35, v135
	v_mul_f32_e32 v36, v36, v136
	v_mul_f32_e32 v37, v37, v137
	v_cvt_pk_bf16_f32 v38, v38, v39
	v_cvt_pk_bf16_f32 v39, v40, v41
	v_cvt_pk_bf16_f32 v40, v34, v35
	v_cvt_pk_bf16_f32 v41, v36, v37
	global_store_dwordx4 v139, v[38:41], s[66:67]
	s_add_u32 s66, s66, 0x4000
	s_addc_u32 s67, s67, 0
	v_mul_f32_e32 v130, v30, v30
	v_mul_f32_e32 v131, v31, v31
	v_mul_f32_e32 v132, v32, v32
	v_mul_f32_e32 v133, v33, v33
	v_mul_f32_e32 v134, v26, v26
	v_mul_f32_e32 v135, v27, v27
	v_mul_f32_e32 v136, v28, v28
	v_mul_f32_e32 v137, v29, v29
	v_fmamk_f32 v130, v130, 0xbdd2d3e7, v138
	v_fmamk_f32 v131, v131, 0xbdd2d3e7, v138
	v_fmamk_f32 v132, v132, 0xbdd2d3e7, v138
	v_fmamk_f32 v133, v133, 0xbdd2d3e7, v138
	v_fmamk_f32 v134, v134, 0xbdd2d3e7, v138
	v_fmamk_f32 v135, v135, 0xbdd2d3e7, v138
	v_fmamk_f32 v136, v136, 0xbdd2d3e7, v138
	v_fmamk_f32 v137, v137, 0xbdd2d3e7, v138
	v_mul_f32_e32 v130, v30, v130
	v_mul_f32_e32 v131, v31, v131
	v_mul_f32_e32 v132, v32, v132
	v_mul_f32_e32 v133, v33, v133
	v_mul_f32_e32 v134, v26, v134
	v_mul_f32_e32 v135, v27, v135
	v_mul_f32_e32 v136, v28, v136
	v_mul_f32_e32 v137, v29, v137
	v_exp_f32_e32 v130, v130
	v_exp_f32_e32 v131, v131
	v_exp_f32_e32 v132, v132
	v_exp_f32_e32 v133, v133
	v_exp_f32_e32 v134, v134
	v_exp_f32_e32 v135, v135
	v_exp_f32_e32 v136, v136
	v_exp_f32_e32 v137, v137
	v_add_f32_e32 v130, 1.0, v130
	v_add_f32_e32 v131, 1.0, v131
	v_add_f32_e32 v132, 1.0, v132
	v_add_f32_e32 v133, 1.0, v133
	v_add_f32_e32 v134, 1.0, v134
	v_add_f32_e32 v135, 1.0, v135
	v_add_f32_e32 v136, 1.0, v136
	v_add_f32_e32 v137, 1.0, v137
	v_rcp_f32_e32 v130, v130
	v_rcp_f32_e32 v131, v131
	v_rcp_f32_e32 v132, v132
	v_rcp_f32_e32 v133, v133
	v_rcp_f32_e32 v134, v134
	v_rcp_f32_e32 v135, v135
	v_rcp_f32_e32 v136, v136
	v_rcp_f32_e32 v137, v137
	v_mul_f32_e32 v30, v30, v130
	v_mul_f32_e32 v31, v31, v131
	v_mul_f32_e32 v32, v32, v132
	v_mul_f32_e32 v33, v33, v133
	v_mul_f32_e32 v26, v26, v134
	v_mul_f32_e32 v27, v27, v135
	v_mul_f32_e32 v28, v28, v136
	v_mul_f32_e32 v29, v29, v137
	v_cvt_pk_bf16_f32 v30, v30, v31
	v_cvt_pk_bf16_f32 v31, v32, v33
	v_cvt_pk_bf16_f32 v32, v26, v27
	v_cvt_pk_bf16_f32 v33, v28, v29
	global_store_dwordx4 v139, v[30:33], s[66:67] offset:-4096
	v_mul_f32_e32 v130, v22, v22
	v_mul_f32_e32 v131, v23, v23
	v_mul_f32_e32 v132, v24, v24
	v_mul_f32_e32 v133, v25, v25
	v_mul_f32_e32 v134, v18, v18
	v_mul_f32_e32 v135, v19, v19
	v_mul_f32_e32 v136, v20, v20
	v_mul_f32_e32 v137, v21, v21
	v_fmamk_f32 v130, v130, 0xbdd2d3e7, v138
	v_fmamk_f32 v131, v131, 0xbdd2d3e7, v138
	v_fmamk_f32 v132, v132, 0xbdd2d3e7, v138
	v_fmamk_f32 v133, v133, 0xbdd2d3e7, v138
	v_fmamk_f32 v134, v134, 0xbdd2d3e7, v138
	v_fmamk_f32 v135, v135, 0xbdd2d3e7, v138
	v_fmamk_f32 v136, v136, 0xbdd2d3e7, v138
	v_fmamk_f32 v137, v137, 0xbdd2d3e7, v138
	v_mul_f32_e32 v130, v22, v130
	v_mul_f32_e32 v131, v23, v131
	v_mul_f32_e32 v132, v24, v132
	v_mul_f32_e32 v133, v25, v133
	v_mul_f32_e32 v134, v18, v134
	v_mul_f32_e32 v135, v19, v135
	v_mul_f32_e32 v136, v20, v136
	v_mul_f32_e32 v137, v21, v137
	v_exp_f32_e32 v130, v130
	v_exp_f32_e32 v131, v131
	v_exp_f32_e32 v132, v132
	v_exp_f32_e32 v133, v133
	v_exp_f32_e32 v134, v134
	v_exp_f32_e32 v135, v135
	v_exp_f32_e32 v136, v136
	v_exp_f32_e32 v137, v137
	v_add_f32_e32 v130, 1.0, v130
	v_add_f32_e32 v131, 1.0, v131
	v_add_f32_e32 v132, 1.0, v132
	v_add_f32_e32 v133, 1.0, v133
	v_add_f32_e32 v134, 1.0, v134
	v_add_f32_e32 v135, 1.0, v135
	v_add_f32_e32 v136, 1.0, v136
	v_add_f32_e32 v137, 1.0, v137
	v_rcp_f32_e32 v130, v130
	v_rcp_f32_e32 v131, v131
	v_rcp_f32_e32 v132, v132
	v_rcp_f32_e32 v133, v133
	v_rcp_f32_e32 v134, v134
	v_rcp_f32_e32 v135, v135
	v_rcp_f32_e32 v136, v136
	v_rcp_f32_e32 v137, v137
	v_mul_f32_e32 v22, v22, v130
	v_mul_f32_e32 v23, v23, v131
	v_mul_f32_e32 v24, v24, v132
	v_mul_f32_e32 v25, v25, v133
	v_mul_f32_e32 v18, v18, v134
	v_mul_f32_e32 v19, v19, v135
	v_mul_f32_e32 v20, v20, v136
	v_mul_f32_e32 v21, v21, v137
	v_cvt_pk_bf16_f32 v22, v22, v23
	v_cvt_pk_bf16_f32 v23, v24, v25
	v_cvt_pk_bf16_f32 v24, v18, v19
	v_cvt_pk_bf16_f32 v25, v20, v21
	global_store_dwordx4 v139, v[22:25], s[66:67]
	s_add_u32 s66, s66, 0x4000
	s_addc_u32 s67, s67, 0
	v_mul_f32_e32 v130, v14, v14
	v_mul_f32_e32 v131, v15, v15
	v_mul_f32_e32 v132, v16, v16
	v_mul_f32_e32 v133, v17, v17
	v_mul_f32_e32 v134, v10, v10
	v_mul_f32_e32 v135, v11, v11
	v_mul_f32_e32 v136, v12, v12
	v_mul_f32_e32 v137, v13, v13
	v_fmamk_f32 v130, v130, 0xbdd2d3e7, v138
	v_fmamk_f32 v131, v131, 0xbdd2d3e7, v138
	v_fmamk_f32 v132, v132, 0xbdd2d3e7, v138
	v_fmamk_f32 v133, v133, 0xbdd2d3e7, v138
	v_fmamk_f32 v134, v134, 0xbdd2d3e7, v138
	v_fmamk_f32 v135, v135, 0xbdd2d3e7, v138
	v_fmamk_f32 v136, v136, 0xbdd2d3e7, v138
	v_fmamk_f32 v137, v137, 0xbdd2d3e7, v138
	v_mul_f32_e32 v130, v14, v130
	v_mul_f32_e32 v131, v15, v131
	v_mul_f32_e32 v132, v16, v132
	v_mul_f32_e32 v133, v17, v133
	v_mul_f32_e32 v134, v10, v134
	v_mul_f32_e32 v135, v11, v135
	v_mul_f32_e32 v136, v12, v136
	v_mul_f32_e32 v137, v13, v137
	v_exp_f32_e32 v130, v130
	v_exp_f32_e32 v131, v131
	v_exp_f32_e32 v132, v132
	v_exp_f32_e32 v133, v133
	v_exp_f32_e32 v134, v134
	v_exp_f32_e32 v135, v135
	v_exp_f32_e32 v136, v136
	v_exp_f32_e32 v137, v137
	v_add_f32_e32 v130, 1.0, v130
	v_add_f32_e32 v131, 1.0, v131
	v_add_f32_e32 v132, 1.0, v132
	v_add_f32_e32 v133, 1.0, v133
	v_add_f32_e32 v134, 1.0, v134
	v_add_f32_e32 v135, 1.0, v135
	v_add_f32_e32 v136, 1.0, v136
	v_add_f32_e32 v137, 1.0, v137
	v_rcp_f32_e32 v130, v130
	v_rcp_f32_e32 v131, v131
	v_rcp_f32_e32 v132, v132
	v_rcp_f32_e32 v133, v133
	v_rcp_f32_e32 v134, v134
	v_rcp_f32_e32 v135, v135
	v_rcp_f32_e32 v136, v136
	v_rcp_f32_e32 v137, v137
	v_mul_f32_e32 v14, v14, v130
	v_mul_f32_e32 v15, v15, v131
	v_mul_f32_e32 v16, v16, v132
	v_mul_f32_e32 v17, v17, v133
	v_mul_f32_e32 v10, v10, v134
	v_mul_f32_e32 v11, v11, v135
	v_mul_f32_e32 v12, v12, v136
	v_mul_f32_e32 v13, v13, v137
	v_cvt_pk_bf16_f32 v14, v14, v15
	v_cvt_pk_bf16_f32 v15, v16, v17
	v_cvt_pk_bf16_f32 v16, v10, v11
	v_cvt_pk_bf16_f32 v17, v12, v13
	global_store_dwordx4 v139, v[14:17], s[66:67] offset:-4096
	v_mul_f32_e32 v130, v6, v6
	v_mul_f32_e32 v131, v7, v7
	v_mul_f32_e32 v132, v8, v8
	v_mul_f32_e32 v133, v9, v9
	v_mul_f32_e32 v134, v2, v2
	v_mul_f32_e32 v135, v3, v3
	v_mul_f32_e32 v136, v4, v4
	v_mul_f32_e32 v137, v5, v5
	v_fmamk_f32 v130, v130, 0xbdd2d3e7, v138
	v_fmamk_f32 v131, v131, 0xbdd2d3e7, v138
	v_fmamk_f32 v132, v132, 0xbdd2d3e7, v138
	v_fmamk_f32 v133, v133, 0xbdd2d3e7, v138
	v_fmamk_f32 v134, v134, 0xbdd2d3e7, v138
	v_fmamk_f32 v135, v135, 0xbdd2d3e7, v138
	v_fmamk_f32 v136, v136, 0xbdd2d3e7, v138
	v_fmamk_f32 v137, v137, 0xbdd2d3e7, v138
	v_mul_f32_e32 v130, v6, v130
	v_mul_f32_e32 v131, v7, v131
	v_mul_f32_e32 v132, v8, v132
	v_mul_f32_e32 v133, v9, v133
	v_mul_f32_e32 v134, v2, v134
	v_mul_f32_e32 v135, v3, v135
	v_mul_f32_e32 v136, v4, v136
	v_mul_f32_e32 v137, v5, v137
	v_exp_f32_e32 v130, v130
	v_exp_f32_e32 v131, v131
	v_exp_f32_e32 v132, v132
	v_exp_f32_e32 v133, v133
	v_exp_f32_e32 v134, v134
	v_exp_f32_e32 v135, v135
	v_exp_f32_e32 v136, v136
	v_exp_f32_e32 v137, v137
	v_add_f32_e32 v130, 1.0, v130
	v_add_f32_e32 v131, 1.0, v131
	v_add_f32_e32 v132, 1.0, v132
	v_add_f32_e32 v133, 1.0, v133
	v_add_f32_e32 v134, 1.0, v134
	v_add_f32_e32 v135, 1.0, v135
	v_add_f32_e32 v136, 1.0, v136
	v_add_f32_e32 v137, 1.0, v137
	v_rcp_f32_e32 v130, v130
	v_rcp_f32_e32 v131, v131
	v_rcp_f32_e32 v132, v132
	v_rcp_f32_e32 v133, v133
	v_rcp_f32_e32 v134, v134
	v_rcp_f32_e32 v135, v135
	v_rcp_f32_e32 v136, v136
	v_rcp_f32_e32 v137, v137
	v_mul_f32_e32 v6, v6, v130
	v_mul_f32_e32 v7, v7, v131
	v_mul_f32_e32 v8, v8, v132
	v_mul_f32_e32 v9, v9, v133
	v_mul_f32_e32 v2, v2, v134
	v_mul_f32_e32 v3, v3, v135
	v_mul_f32_e32 v4, v4, v136
	v_mul_f32_e32 v5, v5, v137
	v_cvt_pk_bf16_f32 v6, v6, v7
	v_cvt_pk_bf16_f32 v7, v8, v9
	v_cvt_pk_bf16_f32 v8, v2, v3
	v_cvt_pk_bf16_f32 v9, v4, v5
	global_store_dwordx4 v139, v[6:9], s[66:67]
.Lwing_done:
	s_andn2_b64 vcc, exec, s[6:7]
	s_mov_b64 s[6:7], -1
	s_cbranch_vccnz .LBB0_451
.LBB0_562:
	s_andn2_b64 vcc, exec, s[4:5]
	s_cbranch_vccnz .LBB0_450
	s_barrier
	s_branch .LBB0_450
